# P3 stores (RTB, AU scan columns) sc1, on top of v102
# speedup vs baseline: 1.0138x; 1.0138x over previous
.LBB0_477:
	v_add_co_u32_e32 v6, vcc, 0xfff88000, v2
	v_cvt_pk_bf16_f32 v22, v4, v5
	s_nop 0
	v_addc_co_u32_e32 v7, vcc, -1, v3, vcc
	v_add_co_u32_e32 v18, vcc, 0xfff90000, v2
	v_add_co_u32_e64 v14, s[0:1], s22, v2
	s_nop 0
	v_addc_co_u32_e32 v19, vcc, -1, v3, vcc
	v_add_co_u32_e32 v20, vcc, 0xfff98000, v2
	global_load_dword v43, v[6:7], off nt
	global_load_dword v44, v[18:19], off nt
	v_addc_co_u32_e32 v21, vcc, -1, v3, vcc
	v_add_co_u32_e32 v6, vcc, 0xfffa0000, v2
	v_addc_co_u32_e64 v15, s[0:1], -1, v3, s[0:1]
	s_nop 0
	v_addc_co_u32_e32 v7, vcc, -1, v3, vcc
	v_add_co_u32_e32 v18, vcc, 0xfffa8000, v2
	global_load_dword v45, v[20:21], off nt
	global_load_dword v46, v[6:7], off nt
	v_addc_co_u32_e32 v19, vcc, -1, v3, vcc
	v_add_co_u32_e32 v6, vcc, 0xfffb0000, v2
	v_add_co_u32_e64 v16, s[0:1], s23, v2
	s_nop 0
	v_addc_co_u32_e32 v7, vcc, -1, v3, vcc
	v_add_co_u32_e32 v20, vcc, 0xfffb8000, v2
	global_load_dword v47, v[18:19], off nt
	global_load_dword v48, v[6:7], off nt
	v_addc_co_u32_e32 v21, vcc, -1, v3, vcc
	v_add_co_u32_e32 v6, vcc, 0xfffc0000, v2
	v_addc_co_u32_e64 v17, s[0:1], -1, v3, s[0:1]
	s_nop 0
	v_addc_co_u32_e32 v7, vcc, -1, v3, vcc
	v_add_co_u32_e32 v18, vcc, 0xfffc8000, v2
	global_load_dword v49, v[20:21], off nt
	global_load_dword v50, v[6:7], off nt
	v_addc_co_u32_e32 v19, vcc, -1, v3, vcc
	v_add_co_u32_e32 v6, vcc, 0xfffd0000, v2
	global_load_dword v51, v[18:19], off nt
	s_nop 0
	v_addc_co_u32_e32 v7, vcc, -1, v3, vcc
	v_add_co_u32_e32 v18, vcc, 0xfffd8000, v2
	s_add_i32 s29, s29, 16
	s_nop 0
	v_addc_co_u32_e32 v19, vcc, -1, v3, vcc
	v_add_co_u32_e32 v20, vcc, 0xfffe0000, v2
	global_load_dword v52, v[6:7], off nt
	global_load_dword v53, v[18:19], off nt
	v_addc_co_u32_e32 v21, vcc, -1, v3, vcc
	v_add_co_u32_e32 v6, vcc, 0xfffe8000, v2
	s_cmp_gt_u32 s29, 47
	s_nop 0
	v_addc_co_u32_e32 v7, vcc, -1, v3, vcc
	v_add_co_u32_e32 v18, vcc, 0xffff0000, v2
	global_load_dword v54, v[20:21], off nt
	global_load_dword v55, v[6:7], off nt
	v_addc_co_u32_e32 v19, vcc, -1, v3, vcc
	v_add_co_u32_e32 v6, vcc, 0xffff8000, v2
	s_waitcnt vmcnt(12)
	v_lshlrev_b32_e32 v42, 16, v43
	v_addc_co_u32_e32 v7, vcc, -1, v3, vcc
	global_load_dword v56, v[18:19], off nt
	global_load_dword v57, v[6:7], off nt
	global_load_dword v58, v[2:3], off nt
	v_add_co_u32_e32 v20, vcc, 0xfbf88000, v2
	v_and_b32_e32 v43, 0xffff0000, v43
	s_nop 0
	v_addc_co_u32_e32 v21, vcc, -1, v3, vcc
	v_add_co_u32_e32 v6, vcc, 0xfbf90000, v2
	global_store_dword v[20:21], v22, off sc1
	s_nop 0
	v_addc_co_u32_e32 v7, vcc, -1, v3, vcc
	v_add_co_u32_e32 v18, vcc, 0xfbf98000, v2
	v_pk_fma_f32 v[4:5], v[0:1], v[4:5], v[42:43]
	s_nop 0
	v_addc_co_u32_e32 v19, vcc, -1, v3, vcc
	v_add_co_u32_e32 v20, vcc, 0xfbfa0000, v2
	s_waitcnt vmcnt(15)
	v_lshlrev_b32_e32 v42, 16, v44
	v_addc_co_u32_e32 v21, vcc, -1, v3, vcc
	v_add_co_u32_e32 v22, vcc, 0xfbfa8000, v2
	v_and_b32_e32 v43, 0xffff0000, v44
	s_nop 0
	v_addc_co_u32_e32 v23, vcc, -1, v3, vcc
	v_add_co_u32_e32 v24, vcc, 0xfbfb0000, v2
	v_cvt_pk_bf16_f32 v44, v4, v5
	s_nop 0
	v_addc_co_u32_e32 v25, vcc, -1, v3, vcc
	v_add_co_u32_e32 v26, vcc, 0xfbfb8000, v2
	v_pk_fma_f32 v[4:5], v[0:1], v[4:5], v[42:43]
	s_nop 0
	v_addc_co_u32_e32 v27, vcc, -1, v3, vcc
	s_waitcnt vmcnt(14)
	v_lshlrev_b32_e32 v42, 16, v45
	v_and_b32_e32 v43, 0xffff0000, v45
	v_add_co_u32_e32 v28, vcc, 0xfbfc0000, v2
	global_store_dword v[6:7], v44, off sc1
	v_cvt_pk_bf16_f32 v44, v4, v5
	v_pk_fma_f32 v[4:5], v[0:1], v[4:5], v[42:43]
	s_waitcnt vmcnt(14)
	v_lshlrev_b32_e32 v6, 16, v46
	v_and_b32_e32 v7, 0xffff0000, v46
	v_addc_co_u32_e32 v29, vcc, -1, v3, vcc
	global_store_dword v[18:19], v44, off sc1
	v_cvt_pk_bf16_f32 v18, v4, v5
	v_pk_fma_f32 v[4:5], v[0:1], v[4:5], v[6:7]
	s_waitcnt vmcnt(14)
	v_lshlrev_b32_e32 v6, 16, v47
	v_and_b32_e32 v7, 0xffff0000, v47
	v_add_co_u32_e32 v30, vcc, 0xfbfc8000, v2
	global_store_dword v[20:21], v18, off sc1
	v_cvt_pk_bf16_f32 v18, v4, v5
	v_pk_fma_f32 v[4:5], v[0:1], v[4:5], v[6:7]
	s_waitcnt vmcnt(14)
	v_lshlrev_b32_e32 v6, 16, v48
	v_and_b32_e32 v7, 0xffff0000, v48
	v_addc_co_u32_e32 v31, vcc, -1, v3, vcc
	global_store_dword v[22:23], v18, off sc1
	v_cvt_pk_bf16_f32 v18, v4, v5
	v_pk_fma_f32 v[4:5], v[0:1], v[4:5], v[6:7]
	s_waitcnt vmcnt(14)
	v_lshlrev_b32_e32 v6, 16, v49
	v_and_b32_e32 v7, 0xffff0000, v49
	v_add_co_u32_e32 v32, vcc, 0xfbfd0000, v2
	global_store_dword v[24:25], v18, off sc1
	v_cvt_pk_bf16_f32 v18, v4, v5
	v_pk_fma_f32 v[4:5], v[0:1], v[4:5], v[6:7]
	s_waitcnt vmcnt(14)
	v_lshlrev_b32_e32 v6, 16, v50
	v_and_b32_e32 v7, 0xffff0000, v50
	v_addc_co_u32_e32 v33, vcc, -1, v3, vcc
	global_store_dword v[26:27], v18, off sc1
	v_cvt_pk_bf16_f32 v18, v4, v5
	v_pk_fma_f32 v[4:5], v[0:1], v[4:5], v[6:7]
	s_waitcnt vmcnt(14)
	v_lshlrev_b32_e32 v6, 16, v51
	v_and_b32_e32 v7, 0xffff0000, v51
	v_add_co_u32_e32 v34, vcc, 0xfbfd8000, v2
	global_store_dword v[28:29], v18, off sc1
	v_cvt_pk_bf16_f32 v18, v4, v5
	v_pk_fma_f32 v[4:5], v[0:1], v[4:5], v[6:7]
	s_waitcnt vmcnt(14)
	v_lshlrev_b32_e32 v6, 16, v52
	v_and_b32_e32 v7, 0xffff0000, v52
	v_addc_co_u32_e32 v35, vcc, -1, v3, vcc
	global_store_dword v[30:31], v18, off sc1
	v_cvt_pk_bf16_f32 v18, v4, v5
	v_pk_fma_f32 v[4:5], v[0:1], v[4:5], v[6:7]
	s_waitcnt vmcnt(14)
	v_lshlrev_b32_e32 v6, 16, v53
	v_and_b32_e32 v7, 0xffff0000, v53
	v_add_co_u32_e32 v36, vcc, s26, v2
	global_store_dword v[32:33], v18, off sc1
	v_cvt_pk_bf16_f32 v20, v4, v5
	s_waitcnt vmcnt(14)
	v_lshlrev_b32_e32 v18, 16, v54
	v_and_b32_e32 v19, 0xffff0000, v54
	v_pk_fma_f32 v[4:5], v[0:1], v[4:5], v[6:7]
	v_addc_co_u32_e32 v37, vcc, -1, v3, vcc
	global_store_dword v[34:35], v20, off sc1
	s_waitcnt vmcnt(14)
	v_lshlrev_b32_e32 v6, 16, v55
	v_and_b32_e32 v7, 0xffff0000, v55
	v_cvt_pk_bf16_f32 v20, v4, v5
	v_pk_fma_f32 v[4:5], v[0:1], v[4:5], v[18:19]
	v_add_co_u32_e32 v38, vcc, s27, v2
	s_waitcnt vmcnt(13)
	v_lshlrev_b32_e32 v18, 16, v56
	v_and_b32_e32 v19, 0xffff0000, v56
	global_store_dword v[14:15], v20, off sc1
	v_cvt_pk_bf16_f32 v20, v4, v5
	v_pk_fma_f32 v[4:5], v[0:1], v[4:5], v[6:7]
	v_addc_co_u32_e32 v39, vcc, -1, v3, vcc
	s_waitcnt vmcnt(13)
	v_lshlrev_b32_e32 v6, 16, v57
	v_and_b32_e32 v7, 0xffff0000, v57
	global_store_dword v[16:17], v20, off sc1
	v_cvt_pk_bf16_f32 v16, v4, v5
	v_pk_fma_f32 v[4:5], v[0:1], v[4:5], v[18:19]
	v_add_co_u32_e32 v40, vcc, 0xfc000000, v2
	s_waitcnt vmcnt(13)
	v_lshlrev_b32_e32 v14, 16, v58
	v_and_b32_e32 v15, 0xffff0000, v58
	global_store_dword v[36:37], v16, off sc1
	v_cvt_pk_bf16_f32 v16, v4, v5
	v_pk_fma_f32 v[4:5], v[0:1], v[4:5], v[6:7]
	v_addc_co_u32_e32 v41, vcc, -1, v3, vcc
	v_lshl_add_u64 v[2:3], v[2:3], 0, s[10:11]
	v_cvt_pk_bf16_f32 v6, v4, v5
	v_pk_fma_f32 v[4:5], v[0:1], v[4:5], v[14:15]
	global_store_dword v[38:39], v16, off sc1
	global_store_dword v[40:41], v6, off sc1
	s_cbranch_scc0 .LBB0_477
	v_add_u32_e32 v8, s3, v8
	v_cmp_lt_i32_e32 vcc, s28, v8
	s_or_b64 s[8:9], vcc, s[8:9]
	v_add_u32_e32 v9, s12, v9
	s_andn2_b64 exec, exec, s[8:9]
	s_cbranch_execnz .LBB0_476

.LBB0_482:
	s_or_b64 exec, exec, s[10:11]
	v_mov_b64_e32 v[4:5], s[14:15]
	v_mad_i64_i32 v[4:5], s[0:1], v2, s44, v[4:5]
	v_lshlrev_b32_e32 v0, 1, v82
	v_lshl_add_u64 v[4:5], v[4:5], 0, v[0:1]
	v_cvt_pk_bf16_f32 v0, v39, s0
	global_store_short v[4:5], v3, off offset:1024 sc1
	global_store_short_d16_hi v[4:5], v3, off offset:1152 sc1
	global_store_short v[4:5], v0, off offset:2304 sc1
	v_cvt_pk_bf16_f32 v0, v38, s0
	global_store_short v[4:5], v0, off offset:2432 sc1
	v_cvt_pk_bf16_f32 v0, v41, s0
	global_store_short v[4:5], v0, off offset:3584 sc1
	v_cvt_pk_bf16_f32 v0, v40, s0
	v_lshl_add_u64 v[6:7], v[4:5], 0, s[20:21]
	global_store_short v[4:5], v0, off offset:3712 sc1
	v_cvt_pk_bf16_f32 v0, v43, s0
	global_store_short v[6:7], v0, off offset:3840 sc1
	v_cvt_pk_bf16_f32 v0, v42, s0
	global_store_short v[6:7], v0, off offset:3968 sc1
	v_cvt_pk_bf16_f32 v0, v45, s0
	v_add_co_u32_e64 v2, s[0:1], s43, v4
	s_add_i32 s48, s48, s92
	s_nop 0
	v_addc_co_u32_e64 v3, s[0:1], 0, v5, s[0:1]
	global_store_short v[2:3], v0, off offset:2048 sc1
	s_nop 0
	v_cvt_pk_bf16_f32 v0, v44, s0
	global_store_short v[2:3], v0, off offset:2176 sc1
	v_cvt_pk_bf16_f32 v0, v47, s0
	global_store_short v[2:3], v0, off offset:3328 sc1
	v_cvt_pk_bf16_f32 v0, v46, s0
	global_store_short v[2:3], v0, off offset:3456 sc1
	v_cvt_pk_bf16_f32 v0, v49, s0
	v_add_co_u32_e64 v2, s[0:1], s45, v4
	s_cmpk_gt_i32 s48, 0xff
	s_nop 0
	v_addc_co_u32_e64 v3, s[0:1], 0, v5, s[0:1]
	global_store_short v[2:3], v0, off offset:512 sc1
	s_nop 0
	v_cvt_pk_bf16_f32 v0, v48, s0
	global_store_short v[2:3], v0, off offset:640 sc1
	v_cvt_pk_bf16_f32 v0, v51, s0
	global_store_short v[2:3], v0, off offset:1792 sc1
	v_cvt_pk_bf16_f32 v0, v50, s0
	global_store_short v[2:3], v0, off offset:1920 sc1
	v_cvt_pk_bf16_f32 v0, v53, s0
	global_store_short v[2:3], v0, off offset:3072 sc1
	v_cvt_pk_bf16_f32 v0, v52, s0
	global_store_short v[2:3], v0, off offset:3200 sc1
	v_cvt_pk_bf16_f32 v0, v55, s0
	v_add_co_u32_e64 v2, s[0:1], s46, v4
	s_nop 1
	v_addc_co_u32_e64 v3, s[0:1], 0, v5, s[0:1]
	global_store_short v[2:3], v0, off offset:256 sc1
	s_nop 0
	v_cvt_pk_bf16_f32 v0, v54, s0
	global_store_short v[2:3], v0, off offset:384 sc1
	v_cvt_pk_bf16_f32 v0, v57, s0
	global_store_short v[2:3], v0, off offset:1536 sc1
	v_cvt_pk_bf16_f32 v0, v56, s0
	global_store_short v[2:3], v0, off offset:1664 sc1
	v_cvt_pk_bf16_f32 v0, v59, s0
	global_store_short v[2:3], v0, off offset:2816 sc1
	v_cvt_pk_bf16_f32 v0, v58, s0
	global_store_short v[2:3], v0, off offset:2944 sc1
	v_cvt_pk_bf16_f32 v0, v61, s0
	v_add_co_u32_e64 v2, s[0:1], s47, v4
	s_nop 1
	v_addc_co_u32_e64 v3, s[0:1], 0, v5, s[0:1]
	global_store_short v[2:3], v0, off sc1
	s_nop 0
	v_cvt_pk_bf16_f32 v0, v60, s0
	global_store_short v[2:3], v0, off offset:128 sc1
	v_cvt_pk_bf16_f32 v0, v63, s0
	global_store_short v[2:3], v0, off offset:1280 sc1
	v_cvt_pk_bf16_f32 v0, v62, s0
	global_store_short v[2:3], v0, off offset:1408 sc1
	v_cvt_pk_bf16_f32 v0, v67, s0
	global_store_short v[2:3], v0, off offset:2560 sc1
	v_cvt_pk_bf16_f32 v0, v66, s0
	global_store_short v[2:3], v0, off offset:2688 sc1
	v_cvt_pk_bf16_f32 v0, v69, s0
	global_store_short v[2:3], v0, off offset:3840 sc1
	v_cvt_pk_bf16_f32 v0, v68, s0
	global_store_short v[2:3], v0, off offset:3968 sc1
	s_barrier
	s_cbranch_scc1 .LBB0_500
